# adds: attention V staging threads remapped so 8 lanes read one row's 128 contiguous bytes (8 rows per load instead of 64 scattered 16-byte pieces); LDS transposed image unchanged
# speedup vs baseline: 1.0184x; 1.0157x over previous
; __device__ __forceinline__ int opaque_tid() { int t = threadIdx.x; asm volatile("" : "+v"(t)); return t; }
; #define LAS __attribute__((address_space(3)))
; DI void attn_phase(LAS unsigned char* lds, bf16_t* QKV, float* LSE, const float* qg, const float* kg, const float* relb, int G, int bid) {
;     const int tid = opaque_tid(), lane = tid & 63, w = tid >> 6, fr = lane & 15, fq = lane >> 4;
;     LAS bf16_t* Qs = (LAS bf16_t*)lds;
;     LAS bf16_t* Ks = Qs + 128 * 72;
;     LAS unsigned* Vt32 = (LAS unsigned*)(Ks + 256 * 72);
;     LAS bf16_t* Vt = (LAS bf16_t*)Vt32;
;     LAS float* tab = (LAS float*)(Vt32 + 64 * 132);
;     const int per = (6144 + G - 1) / G; const int u0 = bid * per; int u1 = u0 + per; if (u1 > 6144) u1 = 6144;
;     const int kp2 = tid & 63, vpc = tid >> 6;
;     u32x4 pq[2], pk[2], pv[2];
;     int rn, h, g, d, n; size_t rowbase;
;     if (u0 < u1) { attn_unit_ptrs(u0, rn, h, g, d, n, rowbase);
;         const bf16_t* qp = QKV + (size_t)g * SEC + rowbase * 1024 + h * 64; const bf16_t* kp = qp + 3 * SEC; const bf16_t* vp = qp + 6 * SEC;
; #pragma unroll
;         for (int it = 0; it < 2; ++it) { const int idx = tid + 512 * it, row = idx >> 3, pc = idx & 7; pq[it] = *(const u32x4*)(qp + (size_t)row * 1024 + pc * 8); pk[it] = *(const u32x4*)(kp + (size_t)row * 1024 + pc * 8); }
;         pv[0] = *(const u32x4*)(vp + (size_t)(2 * kp2) * 1024 + vpc * 8); pv[1] = *(const u32x4*)(vp + (size_t)(2 * kp2 + 1) * 1024 + vpc * 8); }
.LBB0_310:
	s_cmp_gt_i32 s34, 1
	s_mov_b64 s[0:1], -1
	s_cbranch_scc0 .LBB0_331
	v_readlane_b32 s0, v251, 25
	v_readlane_b32 s1, v251, 26
	v_mov_b32_e32 v52, v226
	s_andn2_b64 vcc, exec, s[0:1]
	v_readlane_b32 s2, v251, 28
	s_cbranch_vccnz .LBB0_330
	s_waitcnt vmcnt(0)
	v_lshlrev_b32_e32 v0, 3, v52
	v_and_b32_e32 v24, 56, v0
	v_readlane_b32 s0, v251, 31
	v_lshlrev_b32_e32 v112, 1, v24
	v_readlane_b32 s1, v251, 32
	v_add_u32_e32 v41, 0x200, v52
	v_and_b32_e32 v39, 63, v52
	v_lshl_add_u64 v[8:9], s[0:1], 0, v[112:113]
	v_readlane_b32 s0, v251, 29
	v_readlane_b32 s1, v251, 30
	v_ashrrev_i32_e32 v71, 6, v52
	v_lshrrev_b32_e32 v122, 3, v39
	v_and_b32_e32 v123, 7, v52
	v_lshl_add_u32 v122, v71, 3, v122
	v_ashrrev_i32_e32 v26, 3, v52
	v_lshl_add_u64 v[10:11], s[0:1], 0, v[112:113]
	v_ashrrev_i32_e32 v30, 3, v41
	v_readlane_b32 s0, v251, 33
	v_ashrrev_i32_e32 v27, 31, v26
	v_ashrrev_i32_e32 v31, 31, v30
	v_lshlrev_b32_e32 v16, 12, v122
	v_mov_b32_e32 v17, v113
	v_readlane_b32 s1, v251, 34
	v_lshlrev_b32_e32 v36, 3, v123
	v_lshlrev_b64 v[28:29], 11, v[26:27]
	v_lshlrev_b64 v[32:33], 11, v[30:31]
	v_lshl_add_u64 v[16:17], s[0:1], 0, v[16:17]
	v_ashrrev_i32_e32 v37, 31, v36
	v_lshl_add_u64 v[0:1], v[8:9], 0, v[28:29]
	v_lshl_add_u64 v[4:5], v[10:11], 0, v[28:29]
	v_lshl_add_u64 v[8:9], v[8:9], 0, v[32:33]
	v_lshl_add_u64 v[12:13], v[10:11], 0, v[32:33]
	v_lshl_add_u64 v[20:21], v[36:37], 1, v[16:17]
	global_load_dwordx4 v[0:3], v[0:1], off
	s_nop 0
	global_load_dwordx4 v[4:7], v[4:5], off
	s_nop 0
	global_load_dwordx4 v[8:11], v[8:9], off
	s_nop 0
	global_load_dwordx4 v[12:15], v[12:13], off
	s_nop 0
	global_load_dwordx4 v[16:19], v[20:21], off
	s_nop 0
	global_load_dwordx4 v[20:23], v[20:21], off offset:2048
	v_and_b32_e32 v53, 15, v52
	s_movk_i32 s0, 0xa0
	v_lshlrev_b32_e32 v62, 4, v71
	v_lshlrev_b64 v[56:57], 10, v[30:31]
	v_cmp_gt_i32_e64 s[38:39], s0, v52
	v_add_u32_e32 v25, -16, v52
	s_movk_i32 s0, 0x81
	v_or_b32_e32 v44, v62, v53
	v_and_b32_e32 v31, 48, v52
	v_add_u32_e32 v78, 2, v71
	v_add_u32_e32 v85, 4, v71
	v_add_u32_e32 v92, 6, v71
	v_lshl_add_u32 v38, v39, 2, 0
	v_cmp_gt_u32_e64 s[40:41], s0, v25
	s_movk_i32 s0, 0x1080
	v_add_u32_e32 v46, 0, v31
	v_ashrrev_i32_e32 v45, 31, v44
	v_add_u32_e32 v63, 1, v71
	v_lshlrev_b32_e32 v64, 4, v78
	v_add_u32_e32 v65, 3, v71
	v_lshlrev_b32_e32 v66, 4, v85
	v_add_u32_e32 v67, 5, v71
	v_lshlrev_b32_e32 v68, 4, v92
	v_add_u32_e32 v69, 7, v71
	v_add_u32_e32 v99, 8, v71
	v_bfe_u32 v35, v52, 4, 2
	v_lshlrev_b32_e32 v34, 11, v122
	v_readlane_b32 s34, v250, 5
	v_add_u32_e32 v40, 0, v112
	v_lshlrev_b32_e32 v42, 2, v122
	v_mad_u32_u24 v42, v123, s0, v42
	v_mad_u64_u32 v[48:49], s[0:1], v44, s25, v[46:47]
	v_lshlrev_b64 v[50:51], 11, v[44:45]
	v_cmp_gt_u32_e64 s[42:43], 16, v39
	v_ashrrev_i32_e32 v45, 31, v62
	v_mul_lo_u32 v39, v71, s81
	v_lshrrev_b32_e32 v61, 3, v71
	v_and_b32_e32 v106, 0x70, v62
	v_lshrrev_b32_e32 v62, 3, v63
	v_lshlrev_b32_e32 v107, 4, v63
	v_lshrrev_b32_e32 v63, 3, v78
	v_and_b32_e32 v108, 0x70, v64
	v_lshrrev_b32_e32 v64, 3, v65
	v_lshlrev_b32_e32 v109, 4, v65
	v_lshrrev_b32_e32 v65, 3, v85
	v_and_b32_e32 v111, 0x70, v66
	v_lshrrev_b32_e32 v66, 3, v67
	v_lshlrev_b32_e32 v112, 4, v67
	v_lshrrev_b32_e32 v67, 3, v92
	v_and_b32_e32 v116, 0x70, v68
	v_lshrrev_b32_e32 v68, 3, v69
	v_lshlrev_b32_e32 v117, 4, v69
	v_lshrrev_b32_e32 v69, 3, v99
	v_lshlrev_b32_e32 v70, 4, v99
	v_cmp_lt_i32_e64 s[44:45], 7, v71
	v_cmp_lt_i32_e64 s[54:55], 6, v71
	v_cmp_lt_i32_e64 s[56:57], 5, v71
	v_cmp_lt_i32_e64 s[58:59], 4, v71
	v_cmp_lt_i32_e64 s[60:61], 3, v71
	v_cmp_lt_i32_e64 s[62:63], 2, v71
	v_cmp_lt_i32_e64 s[64:65], 1, v71
	v_cmp_lt_i32_e64 s[66:67], 0, v71
	v_cmp_lt_i32_e64 s[68:69], -1, v71
	v_min_i32_e32 v71, 14, v71
	v_min_i32_e32 v78, 14, v78
	v_min_i32_e32 v85, 14, v85
	v_min_i32_e32 v92, 14, v92
	v_min_i32_e32 v99, 14, v99
	v_lshlrev_b64 v[54:55], 10, v[26:27]
	v_lshl_add_u32 v27, v52, 2, s34
	v_or_b32_e32 v31, 16, v53
	v_lshlrev_b32_e32 v110, 2, v35
	v_add_u32_e32 v43, 0x400, v52
	v_add_u32_e32 v47, 0x600, v52
	v_add_u32_e32 v49, 0x800, v52
	v_add_u32_e32 v58, 0xa00, v52
	v_add_u32_e32 v59, 0xc00, v52
	v_add_u32_e32 v52, 0xe00, v52
	v_add_u32_e32 v73, 1, v71
	v_add_u32_e32 v80, 1, v78
	v_add_u32_e32 v87, 1, v85
	v_add_u32_e32 v94, 1, v92
	v_add_u32_e32 v102, 1, v99
	v_sub_u32_e32 v31, v31, v110
	v_ashrrev_i32_e32 v52, 6, v52
	v_and_b32_e32 v118, 0x70, v70
	v_mad_u32_u24 v101, v53, s81, 0
	v_lshrrev_b32_e32 v71, 3, v73
	v_lshlrev_b32_e32 v73, 5, v73
	v_lshrrev_b32_e32 v78, 3, v80
	v_lshlrev_b32_e32 v80, 5, v80
	v_lshrrev_b32_e32 v85, 3, v87
	v_lshlrev_b32_e32 v87, 5, v87
	v_lshrrev_b32_e32 v92, 3, v94
	v_lshlrev_b32_e32 v94, 5, v94
	v_lshrrev_b32_e32 v99, 3, v102
	v_lshlrev_b32_e32 v102, 5, v102
	v_lshlrev_b32_e32 v105, 3, v35
	v_lshl_add_u32 v31, v31, 2, s34
	v_sub_u32_e32 v72, v53, v110
	v_ashrrev_i32_e32 v41, 6, v41
	v_ashrrev_i32_e32 v43, 6, v43
	v_ashrrev_i32_e32 v47, 6, v47
	v_ashrrev_i32_e32 v49, 6, v49
	v_ashrrev_i32_e32 v58, 6, v58
	v_ashrrev_i32_e32 v59, 6, v59
	v_mul_lo_u32 v60, v52, s81
	v_mul_lo_u32 v52, v26, s25
	v_add_u32_e32 v114, 0xd800, v101
	v_lshlrev_b32_e32 v76, 1, v106
	v_and_b32_e32 v77, 0xe0, v73
	v_add_u32_e32 v103, 0x2100, v101
	v_lshlrev_b32_e32 v83, 1, v108
	s_waitcnt lgkmcnt(0)
; DI void attn_phase(LAS unsigned char* lds, bf16_t* QKV, float* LSE, const float* qg, const float* kg, const float* relb, int G, int bid) {
;     ...
;         bf16x8 qf[2];
;         qf[0] = *(const LAS bf16x8*)(Qs + (16 * w + fr) * 72 + 8 * fq); qf[1] = *(const LAS bf16x8*)(Qs + (16 * w + fr) * 72 + 32 + 8 * fq);
;         f32x4 sc[9];
; #pragma unroll
;         for (int i = 0; i < 9; ++i) { const int tau = w + i; const int kr = ((((n + 1 + (tau >> 3)) & 1) << 7) | ((tau & 7) << 4)) + fr; f32x4 acc = (f32x4){0.f, 0.f, 0.f, 0.f};
;             const bf16x8 a0 = *(const LAS bf16x8*)(Ks + kr * 72 + 8 * fq), a1 = *(const LAS bf16x8*)(Ks + kr * 72 + 32 + 8 * fq);
;             acc = __builtin_amdgcn_mfma_f32_16x16x32_bf16(a0, qf[0], acc, 0, 0, 0);
;             acc = __builtin_amdgcn_mfma_f32_16x16x32_bf16(a1, qf[1], acc, 0, 0, 0);
;             sc[i] = acc; }
;         float mx = -INFINITY;
;         const LAS float* tb = tab + (16 + fr - 4 * fq - 3);
;         const int dlt = fr - 4 * fq;
;         float bv[9][4];
; #pragma unroll
;         for (int i = 0; i < 9; ++i)
; #pragma unroll
;             for (int j = 0; j < 4; ++j) bv[i][j] = tb[16 * (8 - i) + (3 - j)];
; #pragma unroll
;         for (int i = 0; i < 9; ++i)
; #pragma unroll
;             for (int j = 0; j < 4; ++j) asm volatile("" : "+v"(bv[i][j]));
; #pragma unroll
;         for (int i = 0; i < 9; ++i) { const bool tv = (n > 0) || (w + i >= 8);
; #pragma unroll
;             for (int j = 0; j < 4; ++j) { bool valid = tv;
;                 if (i == 0) valid = valid && (dlt - j <= 0);
;                 if (i == 8) valid = valid && (dlt - j >= 0);
;                 const float v = valid ? sc[i][j] + bv[i][j] : -INFINITY; sc[i][j] = v; mx = fmaxf(mx, v); } }
;         mx = x16_max(mx); mx = x32_max(mx);
;         float sum = 0.f;
; #pragma unroll
;         for (int i = 0; i < 9; ++i)
; #pragma unroll
;             for (int j = 0; j < 4; ++j) { const float p = __builtin_amdgcn_exp2f(sc[i][j] - mx); sc[i][j] = p; sum += p; }
;         sum = x16_sum(sum); sum = x32_sum(sum);
;         f32x4 o[4];
; #pragma unroll
;         for (int et = 0; et < 4; ++et) o[et] = (f32x4){0.f, 0.f, 0.f, 0.f};
; #pragma unroll
;         for (int pi = 0; pi < 5; ++pi) { const int ia = 2 * pi, ib = (2 * pi + 1 < 9) ? 2 * pi + 1 : 8;
;             u32x4 pw; pw.x = pk2(sc[ia][0], sc[ia][1]); pw.y = pk2(sc[ia][2], sc[ia][3]);
	v_and_b32_e32 v84, 0xe0, v80
	v_lshlrev_b32_e32 v90, 1, v111
	v_and_b32_e32 v91, 0xe0, v87
	v_lshlrev_b32_e32 v97, 1, v116
	v_and_b32_e32 v98, 0xe0, v94
	v_lshlrev_b32_e32 v104, 1, v118
	v_and_b32_e32 v115, 0xe0, v102
	v_mul_lo_u32 v120, v30, s25
	s_movk_i32 s0, 0x70
	v_add_u32_e32 v35, -12, v31
	v_mul_lo_u32 v41, v41, s81
	v_mul_lo_u32 v43, v43, s81
	v_mul_lo_u32 v47, v47, s81
	v_mul_lo_u32 v49, v49, s81
	v_mul_lo_u32 v58, v58, s81
	v_mul_lo_u32 v59, v59, s81
	v_add_u32_e32 v70, -4, v31
	v_cmp_gt_i32_e64 s[46:47], 1, v72
	v_cmp_gt_i32_e64 s[48:49], 2, v72
	v_cmp_gt_i32_e64 s[50:51], 3, v72
	v_cmp_gt_i32_e64 s[52:53], 4, v72
	s_mov_b32 s87, 0
	v_cmp_lt_i32_e64 s[70:71], -1, v72
	v_cmp_lt_i32_e64 s[72:73], 0, v72
	v_cmp_lt_i32_e64 s[74:75], 1, v72
	v_cmp_lt_i32_e64 s[76:77], 2, v72
	v_add3_u32 v72, v101, v76, v105
	v_add3_u32 v73, v101, v77, v105
	v_add3_u32 v74, v103, v76, v105
	v_add3_u32 v75, v103, v77, v105
	v_add3_u32 v76, v114, v76, v105
	v_add3_u32 v77, v114, v77, v105
	v_add3_u32 v79, v101, v83, v105
	v_add3_u32 v80, v101, v84, v105
	v_add3_u32 v81, v103, v83, v105
	v_add3_u32 v82, v103, v84, v105
	v_add3_u32 v83, v114, v83, v105
	v_add3_u32 v84, v114, v84, v105
	v_add3_u32 v86, v101, v90, v105
	v_add3_u32 v87, v101, v91, v105
	v_add3_u32 v88, v103, v90, v105
	v_add3_u32 v89, v103, v91, v105
	v_add3_u32 v90, v114, v90, v105
	v_add3_u32 v91, v114, v91, v105
	v_add3_u32 v93, v101, v97, v105
	v_add3_u32 v94, v101, v98, v105
	v_add3_u32 v95, v103, v97, v105
	v_add3_u32 v96, v103, v98, v105
	v_add3_u32 v97, v114, v97, v105
	v_add3_u32 v98, v114, v98, v105
	v_add3_u32 v100, v101, v104, v105
	v_add3_u32 v101, v101, v115, v105
	v_add3_u32 v102, v103, v104, v105
	v_add3_u32 v103, v103, v115, v105
	v_add3_u32 v104, v114, v104, v105
	v_add3_u32 v105, v114, v115, v105
	v_or_b32_e32 v106, v106, v53
	v_and_or_b32 v107, v107, s0, v53
	v_or_b32_e32 v108, v108, v53
	v_and_or_b32 v109, v109, s0, v53
	v_or_b32_e32 v114, v111, v53
	v_and_or_b32 v115, v112, s0, v53
	v_or_b32_e32 v116, v116, v53
	v_and_or_b32 v117, v117, s0, v53
	v_or_b32_e32 v118, v118, v53
	v_add_u32_e32 v119, v40, v52
	v_add_u32_e32 v120, v40, v120
	v_lshlrev_b64 v[52:53], 1, v[54:55]
	v_lshlrev_b64 v[54:55], 1, v[56:57]
	v_lshlrev_b32_e32 v56, 1, v110
	v_readlane_b32 s78, v251, 27
	s_branch .LBB0_314
